# GEMM K loop: s_setprio 1 moved ahead of the pre-MMA waits+barrier and s_setprio 0 moved behind the post-MMA barrier (nothing but the MFMAs between the two barriers of a compute segment), on top of the
# speedup vs baseline: 1.0401x; 1.0021x over previous
; #define PG8_STAGE(bufoff, gbase, voff) do { _Pragma("unroll") for (int _i = 0; _i < 2; ++_i) \
;         __builtin_amdgcn_global_load_lds((const unsigned*)((const char*)(gbase) + (voff)[_i]), (LAS unsigned*)(lds + (bufoff) + ldsw + _i * 8192), 16, 0, 0); } while (0)
; #define PG8_LDA(dst, b, h) do { _Pragma("unroll") for (int m = 0; m < 4; ++m) _Pragma("unroll") for (int k = 0; k < 2; ++k) dst[m][k] = *(const LAS bf16x8*)(lds + PG8_SA(b, h) + aoff + m * 2048 + k * 1024); } while (0)
; #define PG8_LDB(dst, b, h) do { _Pragma("unroll") for (int n = 0; n < 2; ++n) _Pragma("unroll") for (int k = 0; k < 2; ++k) dst[n][k] = *(const LAS bf16x8*)(lds + PG8_SB(b, h) + boff + n * 2048 + k * 1024); } while (0)
; #define PG8_MMA(ai, bj, At, Bt) do { __builtin_amdgcn_s_setprio(1); _Pragma("unroll") for (int m = 0; m < 4; ++m) _Pragma("unroll") for (int n = 0; n < 2; ++n) _Pragma("unroll") for (int k = 0; k < 2; ++k) \
;         acc[ai][bj][m][n] = __builtin_amdgcn_mfma_f32_16x16x32_bf16(Bt[n][k], At[m][k], acc[ai][bj][m][n], 0, 0, 0); __builtin_amdgcn_s_setprio(0); } while (0)
; #define PG8_WAIT_V(n) asm volatile("s_waitcnt vmcnt(" #n ")" ::: "memory")
; #define PG8_WAIT_L(n) asm volatile("s_waitcnt lgkmcnt(" #n ")" ::: "memory")
; #define PG8_BAR __builtin_amdgcn_s_barrier()
; __device__ __forceinline__ void gemm_phase(const int tid, LAS unsigned char* lds, const Gemm g, const StaticOrder& S, const int mode  , void* Cout, const int ldc, float* rvs, const float* rbs, const float* rbs_tail) {
;     ...
;         for (int t = 0; t < ntu; t += 2) {
;             const bool last = (t == ntu - 2);
;             const char* a1 = cA + (size_t)(t + 1) * kstep;
;             const char* a2 = last ? nA : cA + (size_t)(t + 2) * kstep; const char* b2 = last ? nB : cB + (size_t)(t + 2) * kstep;
;             const char* a3 = a2 + kstep; const char* b3 = b2 + kstep;
;             PG8_LDB(B0, 0, 0); PG8_LDB(B1, 0, 1); PG8_SCHED; PG8_LDA(At, 0, 0); PG8_STAGE(PG8_SA(1, 1), a1 + hstepA, voffA);
;             PG8_WAIT_V(8); PG8_WAIT_L(0); PG8_BAR; PG8_MMA(0, 0, At, B0); PG8_MMA(0, 1, At, B1); PG8_BAR; PG8_SCHED;
;             PG8_LDA(At, 0, 1); PG8_STAGE(PG8_SB(0, 0), b2, voffB); PG8_STAGE(PG8_SB(0, 1), b2 + hstepB, voffB); PG8_STAGE(PG8_SA(0, 0), a2, voffA);
;             PG8_WAIT_V(8); PG8_WAIT_L(0); PG8_BAR; PG8_MMA(1, 0, At, B0); PG8_MMA(1, 1, At, B1); PG8_BAR; PG8_SCHED;
.Lgemm_peel:
	s_add_i32 s72, s68, 2
	s_add_u32 s62, s60, 0x80
	s_addc_u32 s63, s61, 0
	s_add_i32 s73, 0, 0x10000
	s_cmp_eq_u32 s33, s68
	s_cselect_b32 s63, s55, s63
	s_cselect_b32 s62, s54, s62
	v_add_u32_e32 v158, s73, v147
	s_cselect_b32 s75, s57, s53
	s_cselect_b32 s74, s56, s45
	s_add_i32 s68, 0, 0x14000
	ds_read_b128 v[142:145], v158
	ds_read_b128 v[150:153], v158 offset:1024
	ds_read_b128 v[154:157], v158 offset:2048
	ds_read_b128 v[168:171], v158 offset:3072
	v_add_u32_e32 v158, s68, v147
	ds_read_b128 v[172:175], v158
	ds_read_b128 v[176:179], v158 offset:1024
	ds_read_b128 v[180:183], v158 offset:2048
	ds_read_b128 v[184:187], v158 offset:3072
	v_lshl_add_u64 v[158:159], s[60:61], 0, v[138:139]
	s_add_i32 m0, s71, 0xc000
	ds_read_b128 v[188:191], v149
	ds_read_b128 v[212:215], v149 offset:1024
	ds_read_b128 v[216:219], v149 offset:2048
	ds_read_b128 v[220:223], v149 offset:3072
	ds_read_b128 v[224:227], v149 offset:4096
	ds_read_b128 v[228:231], v149 offset:5120
	ds_read_b128 v[232:235], v149 offset:6144
	ds_read_b128 v[236:239], v149 offset:7168
	global_load_lds_dwordx4 v[158:159], off
	v_lshl_add_u64 v[158:159], s[60:61], 0, v[140:141]
	s_add_i32 m0, s71, 0xe000
	s_nop 0
	global_load_lds_dwordx4 v[158:159], off
	s_setprio 1
	s_waitcnt vmcnt(8)
	s_waitcnt lgkmcnt(0)
	s_barrier
	s_waitcnt lgkmcnt(0)
	v_mfma_f32_16x16x32_bf16 v[124:127], v[142:145], v[188:191], 0
	v_mfma_f32_16x16x32_bf16 v[120:123], v[154:157], v[188:191], 0
	v_mfma_f32_16x16x32_bf16 v[116:119], v[142:145], v[216:219], 0
	v_mfma_f32_16x16x32_bf16 v[112:115], v[154:157], v[216:219], 0
	v_mfma_f32_16x16x32_bf16 v[104:107], v[142:145], v[224:227], 0
	v_mfma_f32_16x16x32_bf16 v[96:99], v[154:157], v[224:227], 0
	v_mfma_f32_16x16x32_bf16 v[88:91], v[142:145], v[232:235], 0
	v_mfma_f32_16x16x32_bf16 v[80:83], v[154:157], v[232:235], 0
	v_mfma_f32_16x16x32_bf16 v[124:127], v[150:153], v[212:215], v[124:127]
	v_mfma_f32_16x16x32_bf16 v[120:123], v[168:171], v[212:215], v[120:123]
	v_mfma_f32_16x16x32_bf16 v[116:119], v[150:153], v[220:223], v[116:119]
	v_mfma_f32_16x16x32_bf16 v[112:115], v[168:171], v[220:223], v[112:115]
	v_mfma_f32_16x16x32_bf16 v[104:107], v[150:153], v[228:231], v[104:107]
	v_mfma_f32_16x16x32_bf16 v[96:99], v[168:171], v[228:231], v[96:99]
	v_mfma_f32_16x16x32_bf16 v[88:91], v[150:153], v[236:239], v[88:91]
	v_mfma_f32_16x16x32_bf16 v[80:83], v[168:171], v[236:239], v[80:83]
	s_setprio 0
	s_setprio 1
	v_mfma_f32_16x16x32_bf16 v[108:111], v[172:175], v[188:191], 0
	v_mfma_f32_16x16x32_bf16 v[100:103], v[180:183], v[188:191], 0
	v_mfma_f32_16x16x32_bf16 v[92:95], v[172:175], v[216:219], 0
	v_mfma_f32_16x16x32_bf16 v[84:87], v[180:183], v[216:219], 0
	v_mfma_f32_16x16x32_bf16 v[76:79], v[172:175], v[224:227], 0
	v_mfma_f32_16x16x32_bf16 v[72:75], v[180:183], v[224:227], 0
	v_mfma_f32_16x16x32_bf16 v[68:71], v[172:175], v[232:235], 0
	v_mfma_f32_16x16x32_bf16 v[64:67], v[180:183], v[232:235], 0
	v_mfma_f32_16x16x32_bf16 v[108:111], v[176:179], v[212:215], v[108:111]
	v_mfma_f32_16x16x32_bf16 v[100:103], v[184:187], v[212:215], v[100:103]
	v_mfma_f32_16x16x32_bf16 v[92:95], v[176:179], v[220:223], v[92:95]
	v_mfma_f32_16x16x32_bf16 v[84:87], v[184:187], v[220:223], v[84:87]
	v_mfma_f32_16x16x32_bf16 v[76:79], v[176:179], v[228:231], v[76:79]
	v_mfma_f32_16x16x32_bf16 v[72:75], v[184:187], v[228:231], v[72:75]
	v_mfma_f32_16x16x32_bf16 v[68:71], v[176:179], v[236:239], v[68:71]
	v_mfma_f32_16x16x32_bf16 v[64:67], v[184:187], v[236:239], v[64:67]
	s_barrier
	s_setprio 0
	s_add_i32 s73, s73, s70
	v_lshl_add_u64 v[158:159], s[74:75], 0, v[160:161]
	s_mov_b32 m0, s73
	ds_read_b128 v[188:191], v149 offset:16384
	ds_read_b128 v[212:215], v149 offset:17408
	ds_read_b128 v[216:219], v149 offset:18432
	ds_read_b128 v[220:223], v149 offset:19456
	ds_read_b128 v[224:227], v149 offset:20480
	ds_read_b128 v[228:231], v149 offset:21504
	ds_read_b128 v[232:235], v149 offset:22528
	ds_read_b128 v[236:239], v149 offset:23552
	global_load_lds_dwordx4 v[158:159], off
	s_add_i32 m0, s73, 0x2000
	v_lshl_add_u64 v[192:193], s[74:75], 0, v[132:133]
	s_add_u32 s74, s74, s59
	s_addc_u32 s75, s75, 0
	s_add_i32 s68, s68, s70
	global_load_lds_dwordx4 v[192:193], off
	v_lshl_add_u64 v[194:195], s[74:75], 0, v[160:161]
	s_mov_b32 m0, s68
	v_lshl_add_u64 v[240:241], s[74:75], 0, v[132:133]
	global_load_lds_dwordx4 v[194:195], off
	s_add_i32 m0, s68, 0x2000
	v_lshl_add_u64 v[242:243], s[62:63], 0, v[128:129]
	global_load_lds_dwordx4 v[240:241], off
	s_mov_b32 m0, s71
	v_lshl_add_u64 v[244:245], s[62:63], 0, v[130:131]
	global_load_lds_dwordx4 v[242:243], off
	s_mov_b32 m0, s88
	s_nop 0
	global_load_lds_dwordx4 v[244:245], off
	s_setprio 1
	s_waitcnt vmcnt(8)
	s_waitcnt lgkmcnt(0)
	s_barrier
; #define PG8_STAGE(bufoff, gbase, voff) do { _Pragma("unroll") for (int _i = 0; _i < 2; ++_i) \
;         __builtin_amdgcn_global_load_lds((const unsigned*)((const char*)(gbase) + (voff)[_i]), (LAS unsigned*)(lds + (bufoff) + ldsw + _i * 8192), 16, 0, 0); } while (0)
; #define PG8_LDA(dst, b, h) do { _Pragma("unroll") for (int m = 0; m < 4; ++m) _Pragma("unroll") for (int k = 0; k < 2; ++k) dst[m][k] = *(const LAS bf16x8*)(lds + PG8_SA(b, h) + aoff + m * 2048 + k * 1024); } while (0)
; #define PG8_LDB(dst, b, h) do { _Pragma("unroll") for (int n = 0; n < 2; ++n) _Pragma("unroll") for (int k = 0; k < 2; ++k) dst[n][k] = *(const LAS bf16x8*)(lds + PG8_SB(b, h) + boff + n * 2048 + k * 1024); } while (0)
; #define PG8_MMA(ai, bj, At, Bt) do { __builtin_amdgcn_s_setprio(1); _Pragma("unroll") for (int m = 0; m < 4; ++m) _Pragma("unroll") for (int n = 0; n < 2; ++n) _Pragma("unroll") for (int k = 0; k < 2; ++k) \
;         acc[ai][bj][m][n] = __builtin_amdgcn_mfma_f32_16x16x32_bf16(Bt[n][k], At[m][k], acc[ai][bj][m][n], 0, 0, 0); __builtin_amdgcn_s_setprio(0); } while (0)
; #define PG8_WAIT_V(n) asm volatile("s_waitcnt vmcnt(" #n ")" ::: "memory")
; #define PG8_WAIT_L(n) asm volatile("s_waitcnt lgkmcnt(" #n ")" ::: "memory")
; #define PG8_BAR __builtin_amdgcn_s_barrier()
; #define PG8_SCHED __builtin_amdgcn_sched_barrier(0)
; __device__ __forceinline__ void gemm_phase(const int tid, LAS unsigned char* lds, const Gemm g, const StaticOrder& S, const int mode  , void* Cout, const int ldc, float* rvs, const float* rbs, const float* rbs_tail) {
;     ...
;             PG8_WAIT_V(8); PG8_WAIT_L(0); PG8_BAR; PG8_MMA(0, 0, At, B0); PG8_MMA(0, 1, At, B1); PG8_BAR; PG8_SCHED;
;             PG8_LDA(At, 0, 1); PG8_STAGE(PG8_SB(0, 0), b2, voffB); PG8_STAGE(PG8_SB(0, 1), b2 + hstepB, voffB); PG8_STAGE(PG8_SA(0, 0), a2, voffA);
;             PG8_WAIT_V(8); PG8_WAIT_L(0); PG8_BAR; PG8_MMA(1, 0, At, B0); PG8_MMA(1, 1, At, B1); PG8_BAR; PG8_SCHED;
;             PG8_LDB(B0, 1, 0); PG8_LDB(B1, 1, 1); PG8_SCHED; PG8_LDA(At, 1, 0); PG8_STAGE(PG8_SA(0, 1), a2 + hstepA, voffA);
;             PG8_WAIT_V(8); PG8_WAIT_L(0); PG8_BAR; PG8_MMA(0, 0, At, B0); PG8_MMA(0, 1, At, B1); PG8_BAR; PG8_SCHED;
	s_waitcnt lgkmcnt(0)
	v_mfma_f32_16x16x32_bf16 v[60:63], v[142:145], v[188:191], 0
	v_mfma_f32_16x16x32_bf16 v[56:59], v[154:157], v[188:191], 0
	v_mfma_f32_16x16x32_bf16 v[52:55], v[142:145], v[216:219], 0
	v_mfma_f32_16x16x32_bf16 v[48:51], v[154:157], v[216:219], 0
	v_mfma_f32_16x16x32_bf16 v[36:39], v[142:145], v[224:227], 0
	v_mfma_f32_16x16x32_bf16 v[32:35], v[154:157], v[224:227], 0
	v_mfma_f32_16x16x32_bf16 v[20:23], v[142:145], v[232:235], 0
	v_mfma_f32_16x16x32_bf16 v[16:19], v[154:157], v[232:235], 0
	v_mfma_f32_16x16x32_bf16 v[60:63], v[150:153], v[212:215], v[60:63]
	v_mfma_f32_16x16x32_bf16 v[56:59], v[168:171], v[212:215], v[56:59]
	v_mfma_f32_16x16x32_bf16 v[52:55], v[150:153], v[220:223], v[52:55]
	v_mfma_f32_16x16x32_bf16 v[48:51], v[168:171], v[220:223], v[48:51]
	v_mfma_f32_16x16x32_bf16 v[36:39], v[150:153], v[228:231], v[36:39]
	v_mfma_f32_16x16x32_bf16 v[32:35], v[168:171], v[228:231], v[32:35]
	v_mfma_f32_16x16x32_bf16 v[20:23], v[150:153], v[236:239], v[20:23]
	v_mfma_f32_16x16x32_bf16 v[16:19], v[168:171], v[236:239], v[16:19]
	s_setprio 0
	s_setprio 1
	v_mfma_f32_16x16x32_bf16 v[44:47], v[172:175], v[188:191], 0
	v_mfma_f32_16x16x32_bf16 v[40:43], v[180:183], v[188:191], 0
	v_mfma_f32_16x16x32_bf16 v[28:31], v[172:175], v[216:219], 0
	v_mfma_f32_16x16x32_bf16 v[24:27], v[180:183], v[216:219], 0
	v_mfma_f32_16x16x32_bf16 v[12:15], v[172:175], v[224:227], 0
	v_mfma_f32_16x16x32_bf16 v[8:11], v[180:183], v[224:227], 0
	v_mfma_f32_16x16x32_bf16 v[4:7], v[172:175], v[232:235], 0
	v_mfma_f32_16x16x32_bf16 v[0:3], v[180:183], v[232:235], 0
	v_mfma_f32_16x16x32_bf16 v[44:47], v[176:179], v[212:215], v[44:47]
	v_mfma_f32_16x16x32_bf16 v[40:43], v[184:187], v[212:215], v[40:43]
	v_mfma_f32_16x16x32_bf16 v[28:31], v[176:179], v[220:223], v[28:31]
	v_mfma_f32_16x16x32_bf16 v[24:27], v[184:187], v[220:223], v[24:27]
	v_mfma_f32_16x16x32_bf16 v[12:15], v[176:179], v[228:231], v[12:15]
	v_mfma_f32_16x16x32_bf16 v[8:11], v[184:187], v[228:231], v[8:11]
	v_mfma_f32_16x16x32_bf16 v[4:7], v[176:179], v[236:239], v[4:7]
	v_mfma_f32_16x16x32_bf16 v[0:3], v[184:187], v[236:239], v[0:3]
	s_barrier
	s_setprio 0
	s_add_i32 s68, 0, 0x18000
	v_add_u32_e32 v165, s68, v147
	s_add_i32 s73, 0, 0x1c000
	ds_read_b128 v[142:145], v165
	ds_read_b128 v[150:153], v165 offset:1024
	ds_read_b128 v[154:157], v165 offset:2048
	ds_read_b128 v[168:171], v165 offset:3072
	v_add_u32_e32 v165, s73, v147
	ds_read_b128 v[172:175], v165
	ds_read_b128 v[176:179], v165 offset:1024
	ds_read_b128 v[180:183], v165 offset:2048
	ds_read_b128 v[184:187], v165 offset:3072
	s_add_u32 s62, s62, s46
	s_addc_u32 s63, s63, 0
	s_mov_b32 m0, s89
	v_lshl_add_u64 v[246:247], s[62:63], 0, v[128:129]
	ds_read_b128 v[188:191], v149 offset:32768
	ds_read_b128 v[212:215], v149 offset:33792
	ds_read_b128 v[216:219], v149 offset:34816
	ds_read_b128 v[220:223], v149 offset:35840
	ds_read_b128 v[224:227], v149 offset:36864
	ds_read_b128 v[228:231], v149 offset:37888
	ds_read_b128 v[232:235], v149 offset:38912
	ds_read_b128 v[236:239], v149 offset:39936
	global_load_lds_dwordx4 v[246:247], off
	v_lshl_add_u64 v[246:247], s[62:63], 0, v[130:131]
	s_mov_b32 m0, s90
	s_nop 0
	global_load_lds_dwordx4 v[246:247], off
	s_setprio 1
	s_waitcnt vmcnt(8)
	s_waitcnt lgkmcnt(0)
	s_barrier
	s_waitcnt lgkmcnt(0)
	v_mfma_f32_16x16x32_bf16 v[124:127], v[142:145], v[188:191], v[124:127]
	v_mfma_f32_16x16x32_bf16 v[120:123], v[154:157], v[188:191], v[120:123]
	v_mfma_f32_16x16x32_bf16 v[116:119], v[142:145], v[216:219], v[116:119]
	v_mfma_f32_16x16x32_bf16 v[112:115], v[154:157], v[216:219], v[112:115]
	v_mfma_f32_16x16x32_bf16 v[104:107], v[142:145], v[224:227], v[104:107]
	v_mfma_f32_16x16x32_bf16 v[96:99], v[154:157], v[224:227], v[96:99]
	v_mfma_f32_16x16x32_bf16 v[88:91], v[142:145], v[232:235], v[88:91]
	v_mfma_f32_16x16x32_bf16 v[80:83], v[154:157], v[232:235], v[80:83]
	v_mfma_f32_16x16x32_bf16 v[124:127], v[150:153], v[212:215], v[124:127]
	v_mfma_f32_16x16x32_bf16 v[120:123], v[168:171], v[212:215], v[120:123]
	v_mfma_f32_16x16x32_bf16 v[116:119], v[150:153], v[220:223], v[116:119]
	v_mfma_f32_16x16x32_bf16 v[112:115], v[168:171], v[220:223], v[112:115]
	v_mfma_f32_16x16x32_bf16 v[104:107], v[150:153], v[228:231], v[104:107]
	v_mfma_f32_16x16x32_bf16 v[96:99], v[168:171], v[228:231], v[96:99]
	v_mfma_f32_16x16x32_bf16 v[88:91], v[150:153], v[236:239], v[88:91]
	v_mfma_f32_16x16x32_bf16 v[80:83], v[168:171], v[236:239], v[80:83]
	s_setprio 0
	s_setprio 1
	v_mfma_f32_16x16x32_bf16 v[108:111], v[172:175], v[188:191], v[108:111]
	v_mfma_f32_16x16x32_bf16 v[100:103], v[180:183], v[188:191], v[100:103]
	v_mfma_f32_16x16x32_bf16 v[92:95], v[172:175], v[216:219], v[92:95]
	v_mfma_f32_16x16x32_bf16 v[84:87], v[180:183], v[216:219], v[84:87]
	v_mfma_f32_16x16x32_bf16 v[76:79], v[172:175], v[224:227], v[76:79]
	v_mfma_f32_16x16x32_bf16 v[72:75], v[180:183], v[224:227], v[72:75]
	v_mfma_f32_16x16x32_bf16 v[68:71], v[172:175], v[232:235], v[68:71]
	v_mfma_f32_16x16x32_bf16 v[64:67], v[180:183], v[232:235], v[64:67]
	v_mfma_f32_16x16x32_bf16 v[108:111], v[176:179], v[212:215], v[108:111]
	v_mfma_f32_16x16x32_bf16 v[100:103], v[184:187], v[212:215], v[100:103]
	v_mfma_f32_16x16x32_bf16 v[92:95], v[176:179], v[220:223], v[92:95]
	v_mfma_f32_16x16x32_bf16 v[84:87], v[184:187], v[220:223], v[84:87]
	v_mfma_f32_16x16x32_bf16 v[76:79], v[176:179], v[228:231], v[76:79]
	v_mfma_f32_16x16x32_bf16 v[72:75], v[184:187], v[228:231], v[72:75]
	v_mfma_f32_16x16x32_bf16 v[68:71], v[176:179], v[236:239], v[68:71]
	v_mfma_f32_16x16x32_bf16 v[64:67], v[184:187], v[236:239], v[64:67]
	s_barrier
; #define PG8_STAGE(bufoff, gbase, voff) do { _Pragma("unroll") for (int _i = 0; _i < 2; ++_i) \
;         __builtin_amdgcn_global_load_lds((const unsigned*)((const char*)(gbase) + (voff)[_i]), (LAS unsigned*)(lds + (bufoff) + ldsw + _i * 8192), 16, 0, 0); } while (0)
; #define PG8_LDA(dst, b, h) do { _Pragma("unroll") for (int m = 0; m < 4; ++m) _Pragma("unroll") for (int k = 0; k < 2; ++k) dst[m][k] = *(const LAS bf16x8*)(lds + PG8_SA(b, h) + aoff + m * 2048 + k * 1024); } while (0)
; #define PG8_LDB(dst, b, h) do { _Pragma("unroll") for (int n = 0; n < 2; ++n) _Pragma("unroll") for (int k = 0; k < 2; ++k) dst[n][k] = *(const LAS bf16x8*)(lds + PG8_SB(b, h) + boff + n * 2048 + k * 1024); } while (0)
; #define PG8_MMA(ai, bj, At, Bt) do { __builtin_amdgcn_s_setprio(1); _Pragma("unroll") for (int m = 0; m < 4; ++m) _Pragma("unroll") for (int n = 0; n < 2; ++n) _Pragma("unroll") for (int k = 0; k < 2; ++k) \
;         acc[ai][bj][m][n] = __builtin_amdgcn_mfma_f32_16x16x32_bf16(Bt[n][k], At[m][k], acc[ai][bj][m][n], 0, 0, 0); __builtin_amdgcn_s_setprio(0); } while (0)
; #define PG8_WAIT_V(n) asm volatile("s_waitcnt vmcnt(" #n ")" ::: "memory")
; __device__ __forceinline__ void gemm_phase(const int tid, LAS unsigned char* lds, const Gemm g, const StaticOrder& S, const int mode  , void* Cout, const int ldc, float* rvs, const float* rbs, const float* rbs_tail) {
;     ...
;         for (int t = 0; t < ntu; t += 2) {
;             const bool last = (t == ntu - 2);
;             const char* a1 = cA + (size_t)(t + 1) * kstep;
;             const char* a2 = last ? nA : cA + (size_t)(t + 2) * kstep; const char* b2 = last ? nB : cB + (size_t)(t + 2) * kstep;
;             const char* a3 = a2 + kstep; const char* b3 = b2 + kstep;
;             PG8_LDB(B0, 0, 0); PG8_LDB(B1, 0, 1); PG8_SCHED; PG8_LDA(At, 0, 0); PG8_STAGE(PG8_SA(1, 1), a1 + hstepA, voffA);
;             PG8_WAIT_V(8); PG8_WAIT_L(0); PG8_BAR; PG8_MMA(0, 0, At, B0); PG8_MMA(0, 1, At, B1); PG8_BAR; PG8_SCHED;
;     ...
;             PG8_WAIT_V(8); PG8_WAIT_L(0); PG8_BAR; PG8_MMA(0, 0, At, B0); PG8_MMA(0, 1, At, B1); PG8_BAR; PG8_SCHED;
;             PG8_LDA(At, 1, 1); PG8_STAGE(PG8_SB(1, 0), b3, voffB); PG8_STAGE(PG8_SB(1, 1), b3 + hstepB, voffB); PG8_STAGE(PG8_SA(1, 0), a3, voffA);
;             PG8_WAIT_V(8); PG8_WAIT_L(0); PG8_BAR; PG8_MMA(1, 0, At, B0); PG8_MMA(1, 1, At, B1); PG8_BAR; PG8_SCHED;
;         }
	s_setprio 0
	s_add_i32 s62, s68, s70
	v_lshl_add_u64 v[158:159], v[158:159], 0, s[36:37]
	s_mov_b32 m0, s62
	ds_read_b128 v[188:191], v149 offset:49152
	ds_read_b128 v[212:215], v149 offset:50176
	ds_read_b128 v[216:219], v149 offset:51200
	ds_read_b128 v[220:223], v149 offset:52224
	ds_read_b128 v[224:227], v149 offset:53248
	ds_read_b128 v[228:231], v149 offset:54272
	ds_read_b128 v[232:235], v149 offset:55296
	ds_read_b128 v[236:239], v149 offset:56320
	global_load_lds_dwordx4 v[158:159], off
	v_lshl_add_u64 v[158:159], v[192:193], 0, s[36:37]
	s_add_i32 m0, s62, 0x2000
	s_add_i32 s62, s73, s70
	global_load_lds_dwordx4 v[158:159], off
	v_lshl_add_u64 v[158:159], v[194:195], 0, s[36:37]
	s_mov_b32 m0, s62
	s_nop 0
	global_load_lds_dwordx4 v[158:159], off
	v_lshl_add_u64 v[158:159], v[240:241], 0, s[36:37]
	s_add_i32 m0, s62, 0x2000
	s_nop 0
	global_load_lds_dwordx4 v[158:159], off
	v_lshl_add_u64 v[158:159], v[242:243], 0, s[36:37]
	s_mov_b32 m0, s91
	s_nop 0
	global_load_lds_dwordx4 v[158:159], off
	v_lshl_add_u64 v[158:159], v[244:245], 0, s[36:37]
	s_mov_b32 m0, s16
	s_nop 0
	global_load_lds_dwordx4 v[158:159], off
	s_setprio 1
	s_waitcnt vmcnt(8)
	s_waitcnt lgkmcnt(0)
	s_barrier
	s_waitcnt lgkmcnt(0)
	v_mfma_f32_16x16x32_bf16 v[60:63], v[142:145], v[188:191], v[60:63]
	v_mfma_f32_16x16x32_bf16 v[56:59], v[154:157], v[188:191], v[56:59]
	v_mfma_f32_16x16x32_bf16 v[52:55], v[142:145], v[216:219], v[52:55]
	v_mfma_f32_16x16x32_bf16 v[48:51], v[154:157], v[216:219], v[48:51]
	v_mfma_f32_16x16x32_bf16 v[36:39], v[142:145], v[224:227], v[36:39]
	v_mfma_f32_16x16x32_bf16 v[32:35], v[154:157], v[224:227], v[32:35]
	v_mfma_f32_16x16x32_bf16 v[20:23], v[142:145], v[232:235], v[20:23]
	v_mfma_f32_16x16x32_bf16 v[16:19], v[154:157], v[232:235], v[16:19]
	v_mfma_f32_16x16x32_bf16 v[60:63], v[150:153], v[212:215], v[60:63]
	v_mfma_f32_16x16x32_bf16 v[56:59], v[168:171], v[212:215], v[56:59]
	v_mfma_f32_16x16x32_bf16 v[52:55], v[150:153], v[220:223], v[52:55]
	v_mfma_f32_16x16x32_bf16 v[48:51], v[168:171], v[220:223], v[48:51]
	v_mfma_f32_16x16x32_bf16 v[36:39], v[150:153], v[228:231], v[36:39]
	v_mfma_f32_16x16x32_bf16 v[32:35], v[168:171], v[228:231], v[32:35]
	v_mfma_f32_16x16x32_bf16 v[20:23], v[150:153], v[236:239], v[20:23]
	v_mfma_f32_16x16x32_bf16 v[16:19], v[168:171], v[236:239], v[16:19]
	s_setprio 0
	s_setprio 1
	v_mfma_f32_16x16x32_bf16 v[44:47], v[172:175], v[188:191], v[44:47]
	v_mfma_f32_16x16x32_bf16 v[40:43], v[180:183], v[188:191], v[40:43]
	v_mfma_f32_16x16x32_bf16 v[28:31], v[172:175], v[216:219], v[28:31]
	v_mfma_f32_16x16x32_bf16 v[24:27], v[180:183], v[216:219], v[24:27]
	v_mfma_f32_16x16x32_bf16 v[12:15], v[172:175], v[224:227], v[12:15]
	v_mfma_f32_16x16x32_bf16 v[8:11], v[180:183], v[224:227], v[8:11]
	v_mfma_f32_16x16x32_bf16 v[4:7], v[172:175], v[232:235], v[4:7]
	v_mfma_f32_16x16x32_bf16 v[0:3], v[180:183], v[232:235], v[0:3]
	v_mfma_f32_16x16x32_bf16 v[44:47], v[176:179], v[212:215], v[44:47]
	v_mfma_f32_16x16x32_bf16 v[40:43], v[184:187], v[212:215], v[40:43]
	v_mfma_f32_16x16x32_bf16 v[28:31], v[176:179], v[220:223], v[28:31]
	v_mfma_f32_16x16x32_bf16 v[24:27], v[184:187], v[220:223], v[24:27]
	v_mfma_f32_16x16x32_bf16 v[12:15], v[176:179], v[228:231], v[12:15]
	v_mfma_f32_16x16x32_bf16 v[8:11], v[184:187], v[228:231], v[8:11]
	v_mfma_f32_16x16x32_bf16 v[4:7], v[176:179], v[236:239], v[4:7]
	v_mfma_f32_16x16x32_bf16 v[0:3], v[184:187], v[236:239], v[0:3]
	s_barrier
	s_setprio 0
	s_add_u32 s60, s60, 0x100
	s_addc_u32 s61, s61, 0
	s_add_u32 s45, s45, 0x100
	s_addc_u32 s53, s53, 0
	s_cmp_ge_u32 s72, s3
	s_mov_b32 s68, s72
	s_cbranch_scc0 .LBB0_231
	s_branch .Lgemm_k_done
.LBB0_231:
	s_add_i32 s72, s68, 2
	s_add_u32 s62, s60, 0x80
	s_addc_u32 s63, s61, 0
	s_add_i32 s73, 0, 0x10000
	s_cmp_eq_u32 s33, s68
	s_cselect_b32 s63, s55, s63
	s_cselect_b32 s62, s54, s62
	v_add_u32_e32 v158, s73, v147
	s_cselect_b32 s75, s57, s53
	s_cselect_b32 s74, s56, s45
	s_add_i32 s68, 0, 0x14000
	ds_read_b128 v[142:145], v158
	ds_read_b128 v[150:153], v158 offset:1024
	ds_read_b128 v[154:157], v158 offset:2048
	ds_read_b128 v[168:171], v158 offset:3072
	v_add_u32_e32 v158, s68, v147
	ds_read_b128 v[172:175], v158
	ds_read_b128 v[176:179], v158 offset:1024
	ds_read_b128 v[180:183], v158 offset:2048
	ds_read_b128 v[184:187], v158 offset:3072
	v_lshl_add_u64 v[158:159], s[60:61], 0, v[138:139]
	s_add_i32 m0, s71, 0xc000
	ds_read_b128 v[188:191], v149
	ds_read_b128 v[212:215], v149 offset:1024
	ds_read_b128 v[216:219], v149 offset:2048
	ds_read_b128 v[220:223], v149 offset:3072
	ds_read_b128 v[224:227], v149 offset:4096
	ds_read_b128 v[228:231], v149 offset:5120
	ds_read_b128 v[232:235], v149 offset:6144
	ds_read_b128 v[236:239], v149 offset:7168
	global_load_lds_dwordx4 v[158:159], off
	v_lshl_add_u64 v[158:159], s[60:61], 0, v[140:141]
	s_add_i32 m0, s71, 0xe000
	s_nop 0
	global_load_lds_dwordx4 v[158:159], off
	s_setprio 1
	s_waitcnt vmcnt(8)
	s_waitcnt lgkmcnt(0)
	s_barrier
; #define PG8_STAGE(bufoff, gbase, voff) do { _Pragma("unroll") for (int _i = 0; _i < 2; ++_i) \
;         __builtin_amdgcn_global_load_lds((const unsigned*)((const char*)(gbase) + (voff)[_i]), (LAS unsigned*)(lds + (bufoff) + ldsw + _i * 8192), 16, 0, 0); } while (0)
; #define PG8_LDA(dst, b, h) do { _Pragma("unroll") for (int m = 0; m < 4; ++m) _Pragma("unroll") for (int k = 0; k < 2; ++k) dst[m][k] = *(const LAS bf16x8*)(lds + PG8_SA(b, h) + aoff + m * 2048 + k * 1024); } while (0)
; #define PG8_MMA(ai, bj, At, Bt) do { __builtin_amdgcn_s_setprio(1); _Pragma("unroll") for (int m = 0; m < 4; ++m) _Pragma("unroll") for (int n = 0; n < 2; ++n) _Pragma("unroll") for (int k = 0; k < 2; ++k) \
;         acc[ai][bj][m][n] = __builtin_amdgcn_mfma_f32_16x16x32_bf16(Bt[n][k], At[m][k], acc[ai][bj][m][n], 0, 0, 0); __builtin_amdgcn_s_setprio(0); } while (0)
; #define PG8_WAIT_V(n) asm volatile("s_waitcnt vmcnt(" #n ")" ::: "memory")
; #define PG8_WAIT_L(n) asm volatile("s_waitcnt lgkmcnt(" #n ")" ::: "memory")
; #define PG8_BAR __builtin_amdgcn_s_barrier()
; #define PG8_SCHED __builtin_amdgcn_sched_barrier(0)
; __device__ __forceinline__ void gemm_phase(const int tid, LAS unsigned char* lds, const Gemm g, const StaticOrder& S, const int mode  , void* Cout, const int ldc, float* rvs, const float* rbs, const float* rbs_tail) {
;     ...
;             PG8_WAIT_V(8); PG8_WAIT_L(0); PG8_BAR; PG8_MMA(0, 0, At, B0); PG8_MMA(0, 1, At, B1); PG8_BAR; PG8_SCHED;
;             PG8_LDA(At, 0, 1); PG8_STAGE(PG8_SB(0, 0), b2, voffB); PG8_STAGE(PG8_SB(0, 1), b2 + hstepB, voffB); PG8_STAGE(PG8_SA(0, 0), a2, voffA);
;             PG8_WAIT_V(8); PG8_WAIT_L(0); PG8_BAR; PG8_MMA(1, 0, At, B0); PG8_MMA(1, 1, At, B1); PG8_BAR; PG8_SCHED;
	s_waitcnt lgkmcnt(0)
	v_mfma_f32_16x16x32_bf16 v[124:127], v[142:145], v[188:191], v[124:127]
	v_mfma_f32_16x16x32_bf16 v[120:123], v[154:157], v[188:191], v[120:123]
	v_mfma_f32_16x16x32_bf16 v[116:119], v[142:145], v[216:219], v[116:119]
	v_mfma_f32_16x16x32_bf16 v[112:115], v[154:157], v[216:219], v[112:115]
	v_mfma_f32_16x16x32_bf16 v[104:107], v[142:145], v[224:227], v[104:107]
	v_mfma_f32_16x16x32_bf16 v[96:99], v[154:157], v[224:227], v[96:99]
	v_mfma_f32_16x16x32_bf16 v[88:91], v[142:145], v[232:235], v[88:91]
	v_mfma_f32_16x16x32_bf16 v[80:83], v[154:157], v[232:235], v[80:83]
	v_mfma_f32_16x16x32_bf16 v[124:127], v[150:153], v[212:215], v[124:127]
	v_mfma_f32_16x16x32_bf16 v[120:123], v[168:171], v[212:215], v[120:123]
	v_mfma_f32_16x16x32_bf16 v[116:119], v[150:153], v[220:223], v[116:119]
	v_mfma_f32_16x16x32_bf16 v[112:115], v[168:171], v[220:223], v[112:115]
	v_mfma_f32_16x16x32_bf16 v[104:107], v[150:153], v[228:231], v[104:107]
	v_mfma_f32_16x16x32_bf16 v[96:99], v[168:171], v[228:231], v[96:99]
	v_mfma_f32_16x16x32_bf16 v[88:91], v[150:153], v[236:239], v[88:91]
	v_mfma_f32_16x16x32_bf16 v[80:83], v[168:171], v[236:239], v[80:83]
	s_setprio 0
	s_setprio 1
	v_mfma_f32_16x16x32_bf16 v[108:111], v[172:175], v[188:191], v[108:111]
	v_mfma_f32_16x16x32_bf16 v[100:103], v[180:183], v[188:191], v[100:103]
	v_mfma_f32_16x16x32_bf16 v[92:95], v[172:175], v[216:219], v[92:95]
	v_mfma_f32_16x16x32_bf16 v[84:87], v[180:183], v[216:219], v[84:87]
	v_mfma_f32_16x16x32_bf16 v[76:79], v[172:175], v[224:227], v[76:79]
	v_mfma_f32_16x16x32_bf16 v[72:75], v[180:183], v[224:227], v[72:75]
	v_mfma_f32_16x16x32_bf16 v[68:71], v[172:175], v[232:235], v[68:71]
	v_mfma_f32_16x16x32_bf16 v[64:67], v[180:183], v[232:235], v[64:67]
	v_mfma_f32_16x16x32_bf16 v[108:111], v[176:179], v[212:215], v[108:111]
	v_mfma_f32_16x16x32_bf16 v[100:103], v[184:187], v[212:215], v[100:103]
	v_mfma_f32_16x16x32_bf16 v[92:95], v[176:179], v[220:223], v[92:95]
	v_mfma_f32_16x16x32_bf16 v[84:87], v[184:187], v[220:223], v[84:87]
	v_mfma_f32_16x16x32_bf16 v[76:79], v[176:179], v[228:231], v[76:79]
	v_mfma_f32_16x16x32_bf16 v[72:75], v[184:187], v[228:231], v[72:75]
	v_mfma_f32_16x16x32_bf16 v[68:71], v[176:179], v[236:239], v[68:71]
	v_mfma_f32_16x16x32_bf16 v[64:67], v[184:187], v[236:239], v[64:67]
	s_barrier
	s_setprio 0
	s_add_i32 s73, s73, s70
	v_lshl_add_u64 v[158:159], s[74:75], 0, v[160:161]
	s_mov_b32 m0, s73
	ds_read_b128 v[188:191], v149 offset:16384
	ds_read_b128 v[212:215], v149 offset:17408
	ds_read_b128 v[216:219], v149 offset:18432
	ds_read_b128 v[220:223], v149 offset:19456
	ds_read_b128 v[224:227], v149 offset:20480
	ds_read_b128 v[228:231], v149 offset:21504
	ds_read_b128 v[232:235], v149 offset:22528
	ds_read_b128 v[236:239], v149 offset:23552
	global_load_lds_dwordx4 v[158:159], off
	s_add_i32 m0, s73, 0x2000
	v_lshl_add_u64 v[192:193], s[74:75], 0, v[132:133]
	s_add_u32 s74, s74, s59
	s_addc_u32 s75, s75, 0
	s_add_i32 s68, s68, s70
	global_load_lds_dwordx4 v[192:193], off
	v_lshl_add_u64 v[194:195], s[74:75], 0, v[160:161]
	s_mov_b32 m0, s68
	v_lshl_add_u64 v[240:241], s[74:75], 0, v[132:133]
	global_load_lds_dwordx4 v[194:195], off
	s_add_i32 m0, s68, 0x2000
	v_lshl_add_u64 v[242:243], s[62:63], 0, v[128:129]
	global_load_lds_dwordx4 v[240:241], off
	s_mov_b32 m0, s71
	v_lshl_add_u64 v[244:245], s[62:63], 0, v[130:131]
	global_load_lds_dwordx4 v[242:243], off
	s_mov_b32 m0, s88
	s_nop 0
	global_load_lds_dwordx4 v[244:245], off
	s_setprio 1
	s_waitcnt vmcnt(8)
	s_waitcnt lgkmcnt(0)
	s_barrier
	s_waitcnt lgkmcnt(0)
	v_mfma_f32_16x16x32_bf16 v[60:63], v[142:145], v[188:191], v[60:63]
	v_mfma_f32_16x16x32_bf16 v[56:59], v[154:157], v[188:191], v[56:59]
	v_mfma_f32_16x16x32_bf16 v[52:55], v[142:145], v[216:219], v[52:55]
	v_mfma_f32_16x16x32_bf16 v[48:51], v[154:157], v[216:219], v[48:51]
	v_mfma_f32_16x16x32_bf16 v[36:39], v[142:145], v[224:227], v[36:39]
	v_mfma_f32_16x16x32_bf16 v[32:35], v[154:157], v[224:227], v[32:35]
	v_mfma_f32_16x16x32_bf16 v[20:23], v[142:145], v[232:235], v[20:23]
	v_mfma_f32_16x16x32_bf16 v[16:19], v[154:157], v[232:235], v[16:19]
	v_mfma_f32_16x16x32_bf16 v[60:63], v[150:153], v[212:215], v[60:63]
	v_mfma_f32_16x16x32_bf16 v[56:59], v[168:171], v[212:215], v[56:59]
	v_mfma_f32_16x16x32_bf16 v[52:55], v[150:153], v[220:223], v[52:55]
	v_mfma_f32_16x16x32_bf16 v[48:51], v[168:171], v[220:223], v[48:51]
	v_mfma_f32_16x16x32_bf16 v[36:39], v[150:153], v[228:231], v[36:39]
	v_mfma_f32_16x16x32_bf16 v[32:35], v[168:171], v[228:231], v[32:35]
	v_mfma_f32_16x16x32_bf16 v[20:23], v[150:153], v[236:239], v[20:23]
	v_mfma_f32_16x16x32_bf16 v[16:19], v[168:171], v[236:239], v[16:19]
	s_setprio 0
	s_setprio 1
	v_mfma_f32_16x16x32_bf16 v[44:47], v[172:175], v[188:191], v[44:47]
	v_mfma_f32_16x16x32_bf16 v[40:43], v[180:183], v[188:191], v[40:43]
	v_mfma_f32_16x16x32_bf16 v[28:31], v[172:175], v[216:219], v[28:31]
	v_mfma_f32_16x16x32_bf16 v[24:27], v[180:183], v[216:219], v[24:27]
	v_mfma_f32_16x16x32_bf16 v[12:15], v[172:175], v[224:227], v[12:15]
	v_mfma_f32_16x16x32_bf16 v[8:11], v[180:183], v[224:227], v[8:11]
	v_mfma_f32_16x16x32_bf16 v[4:7], v[172:175], v[232:235], v[4:7]
	v_mfma_f32_16x16x32_bf16 v[0:3], v[180:183], v[232:235], v[0:3]
	v_mfma_f32_16x16x32_bf16 v[44:47], v[176:179], v[212:215], v[44:47]
	v_mfma_f32_16x16x32_bf16 v[40:43], v[184:187], v[212:215], v[40:43]
	v_mfma_f32_16x16x32_bf16 v[28:31], v[176:179], v[220:223], v[28:31]
	v_mfma_f32_16x16x32_bf16 v[24:27], v[184:187], v[220:223], v[24:27]
	v_mfma_f32_16x16x32_bf16 v[12:15], v[176:179], v[228:231], v[12:15]
	v_mfma_f32_16x16x32_bf16 v[8:11], v[184:187], v[228:231], v[8:11]
	v_mfma_f32_16x16x32_bf16 v[4:7], v[176:179], v[236:239], v[4:7]
	v_mfma_f32_16x16x32_bf16 v[0:3], v[184:187], v[236:239], v[0:3]
	s_barrier
; #define PG8_STAGE(bufoff, gbase, voff) do { _Pragma("unroll") for (int _i = 0; _i < 2; ++_i) \
;         __builtin_amdgcn_global_load_lds((const unsigned*)((const char*)(gbase) + (voff)[_i]), (LAS unsigned*)(lds + (bufoff) + ldsw + _i * 8192), 16, 0, 0); } while (0)
; #define PG8_LDA(dst, b, h) do { _Pragma("unroll") for (int m = 0; m < 4; ++m) _Pragma("unroll") for (int k = 0; k < 2; ++k) dst[m][k] = *(const LAS bf16x8*)(lds + PG8_SA(b, h) + aoff + m * 2048 + k * 1024); } while (0)
; #define PG8_LDB(dst, b, h) do { _Pragma("unroll") for (int n = 0; n < 2; ++n) _Pragma("unroll") for (int k = 0; k < 2; ++k) dst[n][k] = *(const LAS bf16x8*)(lds + PG8_SB(b, h) + boff + n * 2048 + k * 1024); } while (0)
; #define PG8_MMA(ai, bj, At, Bt) do { __builtin_amdgcn_s_setprio(1); _Pragma("unroll") for (int m = 0; m < 4; ++m) _Pragma("unroll") for (int n = 0; n < 2; ++n) _Pragma("unroll") for (int k = 0; k < 2; ++k) \
;         acc[ai][bj][m][n] = __builtin_amdgcn_mfma_f32_16x16x32_bf16(Bt[n][k], At[m][k], acc[ai][bj][m][n], 0, 0, 0); __builtin_amdgcn_s_setprio(0); } while (0)
; #define PG8_WAIT_V(n) asm volatile("s_waitcnt vmcnt(" #n ")" ::: "memory")
; #define PG8_WAIT_L(n) asm volatile("s_waitcnt lgkmcnt(" #n ")" ::: "memory")
; #define PG8_BAR __builtin_amdgcn_s_barrier()
; #define PG8_SCHED __builtin_amdgcn_sched_barrier(0)
; __device__ __forceinline__ void gemm_phase(const int tid, LAS unsigned char* lds, const Gemm g, const StaticOrder& S, const int mode  , void* Cout, const int ldc, float* rvs, const float* rbs, const float* rbs_tail) {
;     ...
;             PG8_WAIT_V(8); PG8_WAIT_L(0); PG8_BAR; PG8_MMA(1, 0, At, B0); PG8_MMA(1, 1, At, B1); PG8_BAR; PG8_SCHED;
;             PG8_LDB(B0, 1, 0); PG8_LDB(B1, 1, 1); PG8_SCHED; PG8_LDA(At, 1, 0); PG8_STAGE(PG8_SA(0, 1), a2 + hstepA, voffA);
;             PG8_WAIT_V(8); PG8_WAIT_L(0); PG8_BAR; PG8_MMA(0, 0, At, B0); PG8_MMA(0, 1, At, B1); PG8_BAR; PG8_SCHED;
	s_setprio 0
	s_add_i32 s68, 0, 0x18000
	v_add_u32_e32 v165, s68, v147
	s_add_i32 s73, 0, 0x1c000
	ds_read_b128 v[142:145], v165
	ds_read_b128 v[150:153], v165 offset:1024
	ds_read_b128 v[154:157], v165 offset:2048
	ds_read_b128 v[168:171], v165 offset:3072
	v_add_u32_e32 v165, s73, v147
	ds_read_b128 v[172:175], v165
	ds_read_b128 v[176:179], v165 offset:1024
	ds_read_b128 v[180:183], v165 offset:2048
	ds_read_b128 v[184:187], v165 offset:3072
	s_add_u32 s62, s62, s46
	s_addc_u32 s63, s63, 0
	s_mov_b32 m0, s89
	v_lshl_add_u64 v[246:247], s[62:63], 0, v[128:129]
	ds_read_b128 v[188:191], v149 offset:32768
	ds_read_b128 v[212:215], v149 offset:33792
	ds_read_b128 v[216:219], v149 offset:34816
	ds_read_b128 v[220:223], v149 offset:35840
	ds_read_b128 v[224:227], v149 offset:36864
	ds_read_b128 v[228:231], v149 offset:37888
	ds_read_b128 v[232:235], v149 offset:38912
	ds_read_b128 v[236:239], v149 offset:39936
	global_load_lds_dwordx4 v[246:247], off
	v_lshl_add_u64 v[246:247], s[62:63], 0, v[130:131]
	s_mov_b32 m0, s90
	s_nop 0
	global_load_lds_dwordx4 v[246:247], off
	s_setprio 1
	s_waitcnt vmcnt(8)
	s_waitcnt lgkmcnt(0)
	s_barrier
	s_waitcnt lgkmcnt(0)
	v_mfma_f32_16x16x32_bf16 v[124:127], v[142:145], v[188:191], v[124:127]
	v_mfma_f32_16x16x32_bf16 v[120:123], v[154:157], v[188:191], v[120:123]
	v_mfma_f32_16x16x32_bf16 v[116:119], v[142:145], v[216:219], v[116:119]
	v_mfma_f32_16x16x32_bf16 v[112:115], v[154:157], v[216:219], v[112:115]
	v_mfma_f32_16x16x32_bf16 v[104:107], v[142:145], v[224:227], v[104:107]
	v_mfma_f32_16x16x32_bf16 v[96:99], v[154:157], v[224:227], v[96:99]
	v_mfma_f32_16x16x32_bf16 v[88:91], v[142:145], v[232:235], v[88:91]
	v_mfma_f32_16x16x32_bf16 v[80:83], v[154:157], v[232:235], v[80:83]
	v_mfma_f32_16x16x32_bf16 v[124:127], v[150:153], v[212:215], v[124:127]
	v_mfma_f32_16x16x32_bf16 v[120:123], v[168:171], v[212:215], v[120:123]
	v_mfma_f32_16x16x32_bf16 v[116:119], v[150:153], v[220:223], v[116:119]
	v_mfma_f32_16x16x32_bf16 v[112:115], v[168:171], v[220:223], v[112:115]
	v_mfma_f32_16x16x32_bf16 v[104:107], v[150:153], v[228:231], v[104:107]
	v_mfma_f32_16x16x32_bf16 v[96:99], v[168:171], v[228:231], v[96:99]
	v_mfma_f32_16x16x32_bf16 v[88:91], v[150:153], v[236:239], v[88:91]
	v_mfma_f32_16x16x32_bf16 v[80:83], v[168:171], v[236:239], v[80:83]
	s_setprio 0
	s_setprio 1
	v_mfma_f32_16x16x32_bf16 v[108:111], v[172:175], v[188:191], v[108:111]
	v_mfma_f32_16x16x32_bf16 v[100:103], v[180:183], v[188:191], v[100:103]
	v_mfma_f32_16x16x32_bf16 v[92:95], v[172:175], v[216:219], v[92:95]
	v_mfma_f32_16x16x32_bf16 v[84:87], v[180:183], v[216:219], v[84:87]
	v_mfma_f32_16x16x32_bf16 v[76:79], v[172:175], v[224:227], v[76:79]
	v_mfma_f32_16x16x32_bf16 v[72:75], v[180:183], v[224:227], v[72:75]
	v_mfma_f32_16x16x32_bf16 v[68:71], v[172:175], v[232:235], v[68:71]
	v_mfma_f32_16x16x32_bf16 v[64:67], v[180:183], v[232:235], v[64:67]
	v_mfma_f32_16x16x32_bf16 v[108:111], v[176:179], v[212:215], v[108:111]
	v_mfma_f32_16x16x32_bf16 v[100:103], v[184:187], v[212:215], v[100:103]
	v_mfma_f32_16x16x32_bf16 v[92:95], v[176:179], v[220:223], v[92:95]
	v_mfma_f32_16x16x32_bf16 v[84:87], v[184:187], v[220:223], v[84:87]
	v_mfma_f32_16x16x32_bf16 v[76:79], v[176:179], v[228:231], v[76:79]
	v_mfma_f32_16x16x32_bf16 v[72:75], v[184:187], v[228:231], v[72:75]
	v_mfma_f32_16x16x32_bf16 v[68:71], v[176:179], v[236:239], v[68:71]
	v_mfma_f32_16x16x32_bf16 v[64:67], v[184:187], v[236:239], v[64:67]
	s_barrier
; #define PG8_STAGE(bufoff, gbase, voff) do { _Pragma("unroll") for (int _i = 0; _i < 2; ++_i) \
;         __builtin_amdgcn_global_load_lds((const unsigned*)((const char*)(gbase) + (voff)[_i]), (LAS unsigned*)(lds + (bufoff) + ldsw + _i * 8192), 16, 0, 0); } while (0)
; #define PG8_LDA(dst, b, h) do { _Pragma("unroll") for (int m = 0; m < 4; ++m) _Pragma("unroll") for (int k = 0; k < 2; ++k) dst[m][k] = *(const LAS bf16x8*)(lds + PG8_SA(b, h) + aoff + m * 2048 + k * 1024); } while (0)
; #define PG8_MMA(ai, bj, At, Bt) do { __builtin_amdgcn_s_setprio(1); _Pragma("unroll") for (int m = 0; m < 4; ++m) _Pragma("unroll") for (int n = 0; n < 2; ++n) _Pragma("unroll") for (int k = 0; k < 2; ++k) \
;         acc[ai][bj][m][n] = __builtin_amdgcn_mfma_f32_16x16x32_bf16(Bt[n][k], At[m][k], acc[ai][bj][m][n], 0, 0, 0); __builtin_amdgcn_s_setprio(0); } while (0)
; #define PG8_WAIT_V(n) asm volatile("s_waitcnt vmcnt(" #n ")" ::: "memory")
; #define PG8_WAIT_L(n) asm volatile("s_waitcnt lgkmcnt(" #n ")" ::: "memory")
; #define PG8_BAR __builtin_amdgcn_s_barrier()
; #define PG8_SCHED __builtin_amdgcn_sched_barrier(0)
; __device__ __forceinline__ void gemm_phase(const int tid, LAS unsigned char* lds, const Gemm g, const StaticOrder& S, const int mode  , void* Cout, const int ldc, float* rvs, const float* rbs, const float* rbs_tail) {
;     ...
;             PG8_WAIT_V(8); PG8_WAIT_L(0); PG8_BAR; PG8_MMA(0, 0, At, B0); PG8_MMA(0, 1, At, B1); PG8_BAR; PG8_SCHED;
;             PG8_LDA(At, 1, 1); PG8_STAGE(PG8_SB(1, 0), b3, voffB); PG8_STAGE(PG8_SB(1, 1), b3 + hstepB, voffB); PG8_STAGE(PG8_SA(1, 0), a3, voffA);
;             PG8_WAIT_V(8); PG8_WAIT_L(0); PG8_BAR; PG8_MMA(1, 0, At, B0); PG8_MMA(1, 1, At, B1); PG8_BAR; PG8_SCHED;
;         }
	s_setprio 0
	s_add_i32 s62, s68, s70
	v_lshl_add_u64 v[158:159], v[158:159], 0, s[36:37]
	s_mov_b32 m0, s62
	ds_read_b128 v[188:191], v149 offset:49152
	ds_read_b128 v[212:215], v149 offset:50176
	ds_read_b128 v[216:219], v149 offset:51200
	ds_read_b128 v[220:223], v149 offset:52224
	ds_read_b128 v[224:227], v149 offset:53248
	ds_read_b128 v[228:231], v149 offset:54272
	ds_read_b128 v[232:235], v149 offset:55296
	ds_read_b128 v[236:239], v149 offset:56320
	global_load_lds_dwordx4 v[158:159], off
	v_lshl_add_u64 v[158:159], v[192:193], 0, s[36:37]
	s_add_i32 m0, s62, 0x2000
	s_add_i32 s62, s73, s70
	global_load_lds_dwordx4 v[158:159], off
	v_lshl_add_u64 v[158:159], v[194:195], 0, s[36:37]
	s_mov_b32 m0, s62
	s_nop 0
	global_load_lds_dwordx4 v[158:159], off
	v_lshl_add_u64 v[158:159], v[240:241], 0, s[36:37]
	s_add_i32 m0, s62, 0x2000
	s_nop 0
	global_load_lds_dwordx4 v[158:159], off
	v_lshl_add_u64 v[158:159], v[242:243], 0, s[36:37]
	s_mov_b32 m0, s91
	s_nop 0
	global_load_lds_dwordx4 v[158:159], off
	v_lshl_add_u64 v[158:159], v[244:245], 0, s[36:37]
	s_mov_b32 m0, s16
	s_nop 0
	global_load_lds_dwordx4 v[158:159], off
	s_setprio 1
	s_waitcnt vmcnt(8)
	s_waitcnt lgkmcnt(0)
	s_barrier
	s_waitcnt lgkmcnt(0)
	v_mfma_f32_16x16x32_bf16 v[60:63], v[142:145], v[188:191], v[60:63]
	v_mfma_f32_16x16x32_bf16 v[56:59], v[154:157], v[188:191], v[56:59]
	v_mfma_f32_16x16x32_bf16 v[52:55], v[142:145], v[216:219], v[52:55]
	v_mfma_f32_16x16x32_bf16 v[48:51], v[154:157], v[216:219], v[48:51]
	v_mfma_f32_16x16x32_bf16 v[36:39], v[142:145], v[224:227], v[36:39]
	v_mfma_f32_16x16x32_bf16 v[32:35], v[154:157], v[224:227], v[32:35]
	v_mfma_f32_16x16x32_bf16 v[20:23], v[142:145], v[232:235], v[20:23]
	v_mfma_f32_16x16x32_bf16 v[16:19], v[154:157], v[232:235], v[16:19]
	v_mfma_f32_16x16x32_bf16 v[60:63], v[150:153], v[212:215], v[60:63]
	v_mfma_f32_16x16x32_bf16 v[56:59], v[168:171], v[212:215], v[56:59]
	v_mfma_f32_16x16x32_bf16 v[52:55], v[150:153], v[220:223], v[52:55]
	v_mfma_f32_16x16x32_bf16 v[48:51], v[168:171], v[220:223], v[48:51]
	v_mfma_f32_16x16x32_bf16 v[36:39], v[150:153], v[228:231], v[36:39]
	v_mfma_f32_16x16x32_bf16 v[32:35], v[168:171], v[228:231], v[32:35]
	v_mfma_f32_16x16x32_bf16 v[20:23], v[150:153], v[236:239], v[20:23]
	v_mfma_f32_16x16x32_bf16 v[16:19], v[168:171], v[236:239], v[16:19]
	s_setprio 0
	s_setprio 1
	v_mfma_f32_16x16x32_bf16 v[44:47], v[172:175], v[188:191], v[44:47]
	v_mfma_f32_16x16x32_bf16 v[40:43], v[180:183], v[188:191], v[40:43]
	v_mfma_f32_16x16x32_bf16 v[28:31], v[172:175], v[216:219], v[28:31]
	v_mfma_f32_16x16x32_bf16 v[24:27], v[180:183], v[216:219], v[24:27]
	v_mfma_f32_16x16x32_bf16 v[12:15], v[172:175], v[224:227], v[12:15]
	v_mfma_f32_16x16x32_bf16 v[8:11], v[180:183], v[224:227], v[8:11]
	v_mfma_f32_16x16x32_bf16 v[4:7], v[172:175], v[232:235], v[4:7]
	v_mfma_f32_16x16x32_bf16 v[0:3], v[180:183], v[232:235], v[0:3]
	v_mfma_f32_16x16x32_bf16 v[44:47], v[176:179], v[212:215], v[44:47]
	v_mfma_f32_16x16x32_bf16 v[40:43], v[184:187], v[212:215], v[40:43]
	v_mfma_f32_16x16x32_bf16 v[28:31], v[176:179], v[220:223], v[28:31]
	v_mfma_f32_16x16x32_bf16 v[24:27], v[184:187], v[220:223], v[24:27]
	v_mfma_f32_16x16x32_bf16 v[12:15], v[176:179], v[228:231], v[12:15]
	v_mfma_f32_16x16x32_bf16 v[8:11], v[184:187], v[228:231], v[8:11]
	v_mfma_f32_16x16x32_bf16 v[4:7], v[176:179], v[236:239], v[4:7]
	v_mfma_f32_16x16x32_bf16 v[0:3], v[184:187], v[236:239], v[0:3]
	s_barrier
	s_setprio 0
	s_add_u32 s60, s60, 0x100
	s_addc_u32 s61, s61, 0
	s_add_u32 s45, s45, 0x100
	s_addc_u32 s53, s53, 0
	s_cmp_ge_u32 s72, s3
	s_mov_b32 s68, s72
	s_cbranch_scc0 .LBB0_231
